# P5->P6 and P6->P7 barriers replaced by per-row-group (bx%8) single-level barriers: producers and consumers of those phases are the same 32 workgroups
# baseline (speedup 1.0000x reference)
.LBB0_820:
	s_waitcnt vmcnt(0)
	s_waitcnt lgkmcnt(0)
	s_barrier
	s_mov_b64 s[0:1], exec
	v_cmp_eq_u32_e32 vcc, 0, v210
	s_and_b64 s[4:5], s[0:1], vcc
	s_mov_b64 exec, s[4:5]
	s_cbranch_execz .LBB0_879
	buffer_wbl2 sc1
	s_waitcnt vmcnt(0)
	s_and_b32 s6, s64, 7
	s_lshl_b32 s6, s6, 6
	s_add_i32 s6, s6, 0x1eb10c00
	s_add_u32 s4, s90, s6
	s_addc_u32 s5, s91, 0
	v_mov_b32_e32 v0, 0
	v_mov_b32_e32 v1, 1
	global_atomic_add v0, v1, s[4:5]
	s_mov_b32 s7, 0
.Lmy_gb5_spin:
	s_waitcnt vmcnt(0)
	global_load_dword v2, v0, s[4:5] sc1
	s_waitcnt vmcnt(0)
	v_readfirstlane_b32 s6, v2
	s_cmp_ge_u32 s6, 32
	s_cbranch_scc1 .Lmy_gb5_done
	s_sleep 1
	s_add_i32 s7, s7, 1
	s_cmp_lt_u32 s7, 0x4000
	s_cbranch_scc1 .Lmy_gb5_spin
.Lmy_gb5_done:
	buffer_inv sc1
.LBB0_879:
	s_or_b64 exec, exec, s[0:1]
	v_mov_b32_e32 v9, v210
	s_barrier
	s_cmpk_gt_i32 s64, 0xaff
	v_readfirstlane_b32 s5, v9
	s_cbranch_scc1 .LBB0_895
	v_lshlrev_b32_e32 v0, 4, v9
	v_add_u32_e32 v1, 0x2000, v0
	v_ashrrev_i32_e32 v2, 31, v1
	v_lshrrev_b32_e32 v2, 22, v2
	v_add_u32_e32 v2, v1, v2
	v_ashrrev_i32_e32 v8, 10, v2
	v_mul_i32_i24_e32 v2, 0x400, v8
	v_sub_u32_e32 v1, v1, v2
	v_lshrrev_b32_e32 v2, 4, v1
	v_bitop3_b32 v1, v2, v1, 32 bitop3:0x6c
	v_ashrrev_i32_e32 v2, 31, v1
	v_lshrrev_b32_e32 v2, 26, v2
	v_add_u32_e32 v2, v1, v2
	v_lshlrev_b32_e32 v3, 3, v8
	v_ashrrev_i32_e32 v10, 6, v2
	v_and_b32_e32 v3, -16, v3
	v_add_u32_e32 v3, v10, v3
	v_and_b32_e32 v4, 3, v10
	s_mov_b32 s0, 0xfffe0
	v_lshrrev_b32_e32 v5, 2, v3
	v_lshlrev_b32_e32 v6, 1, v3
	v_and_b32_e32 v2, 0xc0, v2
	v_and_or_b32 v4, v3, s0, v4
	v_and_b32_e32 v5, 4, v5
	v_and_b32_e32 v6, 24, v6
	v_sub_u32_e32 v1, v1, v2
	v_mov_b32_e32 v2, 1
	v_or3_b32 v4, v4, v5, v6
	v_lshlrev_b32_e32 v5, 5, v8
	v_ashrrev_i16_sdwa v1, v2, sext(v1) dst_sel:DWORD dst_unused:UNUSED_PAD src0_sel:DWORD src1_sel:BYTE_0
	v_and_b32_e32 v5, 32, v5
	v_bfe_i32 v11, v1, 0, 16
	v_add_lshl_u32 v1, v5, v11, 1
	s_waitcnt vmcnt(8)
	v_lshl_add_u32 v128, v4, 12, v1
	v_lshl_add_u32 v130, v3, 12, v1
	v_bfe_i32 v1, v9, 27, 1
	v_lshrrev_b32_e32 v1, 22, v1
	v_add_u32_e32 v1, v0, v1
	v_and_b32_e32 v1, 0xfffffc00, v1
	v_sub_u32_e32 v0, v0, v1
	v_lshrrev_b32_e32 v1, 4, v0
	v_bitop3_b32 v1, v1, v0, 32 bitop3:0x6c
	v_ashrrev_i32_e32 v0, 31, v0
	v_lshrrev_b32_e32 v0, 26, v0
	v_add_u32_e32 v0, v1, v0
	v_ashrrev_i32_e32 v12, 6, v0
	v_ashrrev_i32_e32 v0, 31, v9
	v_lshrrev_b32_e32 v0, 26, v0
	v_add_u32_e32 v0, v9, v0
	v_ashrrev_i32_e32 v13, 6, v0
	v_lshlrev_b32_e32 v0, 3, v13
	s_add_u32 s20, s90, 0x1500000
	v_and_b32_e32 v0, -16, v0
	s_addc_u32 s21, s91, 0
	v_add_u32_e32 v0, v12, v0
	v_and_b32_e32 v3, 3, v12
	s_ashr_i32 s29, s64, 31
	v_and_or_b32 v3, v0, s0, v3
	s_lshr_b32 s0, s29, 29
	s_add_i32 s0, s64, s0
	s_ashr_i32 s8, s5, 6
	s_ashr_i32 s1, s0, 3
	s_and_b32 s0, s0, -8
	s_ashr_i32 s10, s5, 8
	s_lshl_b32 s28, s8, 10
	s_sub_i32 s0, s64, s0
	s_cmp_lt_i32 s0, 0
	s_movk_i32 s30, 0x161
	s_cselect_b32 s4, s30, 0x160
	s_mul_i32 s0, s0, s4
	s_add_i32 s0, s0, s1
	s_mul_hi_i32 s1, s0, 0x2e8ba2e9
	s_lshr_b32 s4, s1, 31
	s_ashr_i32 s1, s1, 6
	s_add_i32 s1, s1, s4
	s_lshl_b32 s6, s1, 3
	s_mulk_i32 s1, 0x160
	s_sub_i32 s0, s0, s1
	s_sext_i32_i16 s1, s0
	s_bfe_u32 s1, s1, 0x3001c
	s_add_i32 s1, s0, s1
	s_sext_i32_i16 s4, s1
	s_and_b32 s1, s1, 0xfff8
	v_lshrrev_b32_e32 v4, 2, v0
	v_lshlrev_b32_e32 v5, 1, v0
	s_sub_i32 s0, s0, s1
	v_and_b32_e32 v4, 4, v4
	v_and_b32_e32 v5, 24, v5
	s_sext_i32_i16 s0, s0
	v_or3_b32 v3, v3, v4, v5
	v_mul_i32_i24_e32 v5, 64, v12
	s_lshr_b32 s4, s4, 3
	s_add_i32 s6, s6, s0
	v_sub_u32_e32 v1, v1, v5
	s_ashr_i32 s7, s6, 31
	s_bfe_i64 s[12:13], s[4:5], 0x100000
	v_lshlrev_b32_e32 v4, 5, v13
	v_ashrrev_i16_sdwa v1, v2, sext(v1) dst_sel:DWORD dst_unused:UNUSED_PAD src0_sel:DWORD src1_sel:BYTE_0
	s_lshl_b64 s[0:1], s[6:7], 20
	s_lshl_b64 s[12:13], s[12:13], 20
	v_and_b32_e32 v4, 32, v4
	v_bfe_i32 v14, v1, 0, 16
	s_add_u32 s26, s20, s12
	v_add_lshl_u32 v1, v4, v14, 1
	s_addc_u32 s27, s21, s13
	s_add_i32 s31, s28, 0
	v_lshl_add_u32 v132, v3, 12, v1
	s_add_i32 m0, s31, 0x10000
	v_lshl_add_u32 v134, v0, 12, v1
	global_load_lds_dwordx4 v132, s[26:27]
	s_add_i32 m0, s31, 0x12000
	s_add_u32 s12, s26, 0x80000
	global_load_lds_dwordx4 v128, s[26:27]
	s_addc_u32 s13, s27, 0
	s_add_i32 m0, s31, 0x14000
	v_mov_b32_e32 v133, 0
	global_load_lds_dwordx4 v132, s[12:13]
	s_add_i32 m0, s31, 0x16000
	s_add_u32 s24, s66, s0
	s_addc_u32 s25, s67, s1
	s_add_i32 s33, s31, 0x2000
	global_load_lds_dwordx4 v128, s[12:13]
	s_mov_b32 m0, s31
	s_add_u32 s0, s24, 0x80000
	global_load_lds_dwordx4 v134, s[24:25]
	s_mov_b32 m0, s33
	s_addc_u32 s1, s25, 0
	s_add_i32 s36, s31, 0x4000
	global_load_lds_dwordx4 v130, s[24:25]
	s_mov_b32 m0, s36
	s_add_i32 s37, s31, 0x6000
	global_load_lds_dwordx4 v134, s[0:1]
	s_mov_b32 m0, s37
	v_mov_b32_e32 v129, v133
	global_load_lds_dwordx4 v130, s[0:1]
	v_mov_b32_e32 v135, v133
	v_mov_b32_e32 v131, v133
	s_cmp_eq_u32 s10, 1
	s_mov_b32 s38, 0
	v_lshl_add_u64 v[6:7], s[26:27], 0, v[132:133]
	v_lshl_add_u64 v[4:5], s[26:27], 0, v[128:129]
	v_lshl_add_u64 v[0:1], s[24:25], 0, v[134:135]
	s_cselect_b64 s[0:1], -1, 0
	s_cmp_lg_u32 s10, 1
	v_lshl_add_u64 v[2:3], s[24:25], 0, v[130:131]
	s_cbranch_scc1 .LBB0_882
	s_barrier

.LBB0_895:
	s_waitcnt vmcnt(0)
	s_waitcnt lgkmcnt(0)
	s_barrier
	s_mov_b64 s[0:1], exec
	v_cmp_eq_u32_e32 vcc, 0, v210
	s_and_b64 s[4:5], s[0:1], vcc
	s_mov_b64 exec, s[4:5]
	s_cbranch_execz .LBB0_954
	buffer_wbl2 sc1
	s_waitcnt vmcnt(0)
	s_and_b32 s6, s64, 7
	s_lshl_b32 s6, s6, 6
	s_add_i32 s6, s6, 0x1eb11000
	s_add_u32 s4, s90, s6
	s_addc_u32 s5, s91, 0
	v_mov_b32_e32 v0, 0
	v_mov_b32_e32 v1, 1
	global_atomic_add v0, v1, s[4:5]
	s_mov_b32 s7, 0

.Lmy_gb6_done:
	buffer_inv sc1
.LBB0_954:
	s_or_b64 exec, exec, s[0:1]
	s_barrier
	s_and_b64 vcc, exec, s[2:3]
	v_readfirstlane_b32 s2, v210
	s_cbranch_vccnz .LBB0_982
	s_ashr_i32 s10, s64, 31
	s_lshr_b32 s0, s10, 29
	s_add_i32 s4, s64, s0
	s_and_b32 s0, s4, -8
	s_sub_i32 s5, s64, s0
	s_cmp_gt_i32 s5, -1
	s_cbranch_scc0 .LBB0_957
	s_lshl_b32 s3, s5, 6
	s_ashr_i32 s4, s4, 3
	s_cbranch_execz .LBB0_958
	s_branch .LBB0_959
